# GEMM MFMA segments: redundant lgkmcnt(0) after the barrier removed, s_setprio 1 hoisted before the pre-barrier waits, s_setprio 0 moved after the closing barrier (fewer non-MFMA slots on the matrix cr
# speedup vs baseline: 1.0131x; 1.0131x over previous
; #define PG8_STAGE(bufoff, gbase, voff) do { _Pragma("unroll") for (int _i = 0; _i < 2; ++_i) \
;         __builtin_amdgcn_global_load_lds((const unsigned*)((const char*)(gbase) + (voff)[_i]), (PG8_LAS unsigned*)(lds + (bufoff) + ldsw + _i * 8192), 16, 0, 0); } while (0)
; #define PG8_LDA(dst, b, h) do { _Pragma("unroll") for (int m = 0; m < 4; ++m) _Pragma("unroll") for (int k = 0; k < 2; ++k) dst[m][k] = *(const PG8_LAS bf16x8*)(lds + PG8_SA(b, h) + aoff + m * 2048 + k * 1024); } while (0)
; #define PG8_LDB(dst, b, h) do { _Pragma("unroll") for (int n = 0; n < 2; ++n) _Pragma("unroll") for (int k = 0; k < 2; ++k) dst[n][k] = *(const PG8_LAS bf16x8*)(lds + PG8_SB(b, h) + boff + n * 2048 + k * 1024); } while (0)
; #define PG8_MMA(ai, bj, At, Bt) do { __builtin_amdgcn_s_setprio(1); _Pragma("unroll") for (int m = 0; m < 4; ++m) _Pragma("unroll") for (int n = 0; n < 2; ++n) _Pragma("unroll") for (int k = 0; k < 2; ++k) \
;         acc[ai][bj][m][n] = __builtin_amdgcn_mfma_f32_16x16x32_bf16(Bt[n][k], At[m][k], acc[ai][bj][m][n], 0, 0, 0); __builtin_amdgcn_s_setprio(0); } while (0)
; #define PG8_WAIT_V(n) asm volatile("s_waitcnt vmcnt(" #n ")" ::: "memory")
; #define PG8_WAIT_L(n) asm volatile("s_waitcnt lgkmcnt(" #n ")" ::: "memory")
; #define PG8_BAR __builtin_amdgcn_s_barrier()
; #define PG8_SCHED __builtin_amdgcn_sched_barrier(0)
; template <class Epi, class Sched, bool ALIGN_EPI = false, bool SP2 = false>
; __device__ __forceinline__ void gemm_phase(PG8_LAS unsigned char* lds, const Gemm g, const Sched& S, const Epi& E) {
;     ...
;         for (int t = 0; t < nt; t += 2) {
;             const bool last = (t == nt - 2);
;             const char* a1 = cA + (size_t)(t + 1) * kstepB;
;             const char* a2 = last ? nA : cA + (size_t)(t + 2) * kstepB; const char* b2 = last ? nB : cB + (size_t)(t + 2) * kstepB;
;             const char* a3 = a2 + kstepB; const char* b3 = b2 + kstepB;
;             if (last && has_next) S.a_ready(nxt);
;             if constexpr (SP2) {
;             PG8_LDB(B0, 0, 0); PG8_LDB(B1, 0, 1); PG8_SCHED; PG8_LDA(At, 0, 0); PG8_STAGE(PG8_SA(1, 1), a1 + hstepB, voffA);
;             PG8_WAIT_V(8); PG8_WAIT_L(0); PG8_BAR; PG8_MMA(0, 0, At, B0); PG8_MMA(0, 1, At, B1); PG8_BAR; PG8_SCHED;
;             PG8_LDA(At, 0, 1); PG8_STAGE(PG8_SB(0, 0), b2, voffB); PG8_STAGE(PG8_SB(0, 1), b2 + hstepB, voffB); PG8_STAGE(PG8_SA(0, 0), a2, voffA);
.LBB0_193:
	s_add_i32 s84, s38, 2
	s_add_u32 s39, s36, 0x4000
	s_addc_u32 s40, s37, 0
	s_cmp_eq_u32 s31, s38
	s_cselect_b32 s42, s8, s39
	s_cselect_b32 s43, s9, s40
	s_cselect_b32 s40, s62, s78
	s_cselect_b32 s41, s63, s82
	s_add_u32 s38, s42, 0x8000
	s_addc_u32 s39, s43, 0
	s_add_i32 s90, 0, 0x10000
	s_add_i32 s64, 0, 0x14000
	v_add_u32_e32 v140, s90, v174
	v_add_u32_e32 v161, s64, v174
	ds_read_b128 v[128:131], v140
	ds_read_b128 v[132:135], v140 offset:1024
	ds_read_b128 v[136:139], v140 offset:2048
	ds_read_b128 v[140:143], v140 offset:3072
	ds_read_b128 v[144:147], v161
	ds_read_b128 v[148:151], v161 offset:1024
	ds_read_b128 v[178:181], v161 offset:2048
	ds_read_b128 v[182:185], v161 offset:3072
	v_lshl_add_u64 v[172:173], s[36:37], 0, v[168:169]
	s_add_i32 m0, s21, 0xc000
	ds_read_b128 v[186:189], v177
	ds_read_b128 v[190:193], v177 offset:1024
	ds_read_b128 v[194:197], v177 offset:2048
	ds_read_b128 v[198:201], v177 offset:3072
	ds_read_b128 v[202:205], v177 offset:4096
	ds_read_b128 v[206:209], v177 offset:5120
	ds_read_b128 v[210:213], v177 offset:6144
	ds_read_b128 v[214:217], v177 offset:7168
	global_load_lds_dwordx4 v[172:173], off
	v_lshl_add_u64 v[172:173], s[36:37], 0, v[170:171]
	s_add_i32 m0, s21, 0xe000
	s_nop 0
	global_load_lds_dwordx4 v[172:173], off
	s_setprio 1
	s_waitcnt vmcnt(8)
	s_waitcnt lgkmcnt(0)
	s_barrier
	v_mfma_f32_16x16x32_bf16 v[124:127], v[128:131], v[186:189], v[124:127]
	v_mfma_f32_16x16x32_bf16 v[124:127], v[132:135], v[190:193], v[124:127]
	v_mfma_f32_16x16x32_bf16 v[120:123], v[136:139], v[186:189], v[120:123]
	v_mfma_f32_16x16x32_bf16 v[120:123], v[140:143], v[190:193], v[120:123]
	v_mfma_f32_16x16x32_bf16 v[108:111], v[128:131], v[194:197], v[108:111]
	v_mfma_f32_16x16x32_bf16 v[108:111], v[132:135], v[198:201], v[108:111]
	v_mfma_f32_16x16x32_bf16 v[104:107], v[136:139], v[194:197], v[104:107]
	v_mfma_f32_16x16x32_bf16 v[104:107], v[140:143], v[198:201], v[104:107]
	v_mfma_f32_16x16x32_bf16 v[92:95], v[128:131], v[202:205], v[92:95]
	v_mfma_f32_16x16x32_bf16 v[92:95], v[132:135], v[206:209], v[92:95]
	v_mfma_f32_16x16x32_bf16 v[88:91], v[136:139], v[202:205], v[88:91]
	v_mfma_f32_16x16x32_bf16 v[88:91], v[140:143], v[206:209], v[88:91]
	v_mfma_f32_16x16x32_bf16 v[76:79], v[128:131], v[210:213], v[76:79]
	v_mfma_f32_16x16x32_bf16 v[76:79], v[132:135], v[214:217], v[76:79]
	v_mfma_f32_16x16x32_bf16 v[72:75], v[136:139], v[210:213], v[72:75]
	v_mfma_f32_16x16x32_bf16 v[72:75], v[140:143], v[214:217], v[72:75]
	s_setprio 0
	s_setprio 1
	v_mfma_f32_16x16x32_bf16 v[116:119], v[144:147], v[186:189], v[116:119]
	v_mfma_f32_16x16x32_bf16 v[116:119], v[148:151], v[190:193], v[116:119]
	v_mfma_f32_16x16x32_bf16 v[112:115], v[178:181], v[186:189], v[112:115]
	v_mfma_f32_16x16x32_bf16 v[112:115], v[182:185], v[190:193], v[112:115]
	v_mfma_f32_16x16x32_bf16 v[100:103], v[144:147], v[194:197], v[100:103]
	v_mfma_f32_16x16x32_bf16 v[100:103], v[148:151], v[198:201], v[100:103]
	v_mfma_f32_16x16x32_bf16 v[96:99], v[178:181], v[194:197], v[96:99]
	v_mfma_f32_16x16x32_bf16 v[96:99], v[182:185], v[198:201], v[96:99]
	v_mfma_f32_16x16x32_bf16 v[84:87], v[144:147], v[202:205], v[84:87]
	v_mfma_f32_16x16x32_bf16 v[84:87], v[148:151], v[206:209], v[84:87]
	v_mfma_f32_16x16x32_bf16 v[80:83], v[178:181], v[202:205], v[80:83]
	v_mfma_f32_16x16x32_bf16 v[80:83], v[182:185], v[206:209], v[80:83]
	v_mfma_f32_16x16x32_bf16 v[68:71], v[144:147], v[210:213], v[68:71]
	v_mfma_f32_16x16x32_bf16 v[68:71], v[148:151], v[214:217], v[68:71]
	v_mfma_f32_16x16x32_bf16 v[64:67], v[178:181], v[210:213], v[64:67]
	v_mfma_f32_16x16x32_bf16 v[64:67], v[182:185], v[214:217], v[64:67]
	s_barrier
	s_setprio 0
	s_add_i32 s65, s90, s20
	v_lshl_add_u64 v[172:173], s[40:41], 0, v[156:157]
	s_mov_b32 m0, s65
	ds_read_b128 v[186:189], v177 offset:16384
	ds_read_b128 v[190:193], v177 offset:17408
	ds_read_b128 v[194:197], v177 offset:18432
	ds_read_b128 v[198:201], v177 offset:19456
	ds_read_b128 v[202:205], v177 offset:20480
	ds_read_b128 v[206:209], v177 offset:21504
	ds_read_b128 v[210:213], v177 offset:22528
	ds_read_b128 v[214:217], v177 offset:23552
	global_load_lds_dwordx4 v[172:173], off
	s_add_i32 m0, s65, 0x2000
	s_add_u32 vcc_lo, s40, 0x4000
	v_lshl_add_u64 v[172:173], s[40:41], 0, v[152:153]
	s_addc_u32 vcc_hi, s41, 0
	s_add_i32 s64, s64, s20
	global_load_lds_dwordx4 v[172:173], off
	v_lshl_add_u64 v[172:173], vcc, 0, v[156:157]
	s_mov_b32 m0, s64
	s_nop 0
	global_load_lds_dwordx4 v[172:173], off
	v_lshl_add_u64 v[172:173], vcc, 0, v[152:153]
	s_add_i32 m0, s64, 0x2000
	s_nop 0
	global_load_lds_dwordx4 v[172:173], off
	v_lshl_add_u64 v[172:173], s[42:43], 0, v[158:159]
	s_mov_b32 m0, s21
	s_nop 0
	global_load_lds_dwordx4 v[172:173], off
	v_lshl_add_u64 v[172:173], s[42:43], 0, v[154:155]
	s_mov_b32 m0, s22
	s_nop 0
	global_load_lds_dwordx4 v[172:173], off
	s_setprio 1
	s_waitcnt vmcnt(8)
	s_waitcnt lgkmcnt(0)
	s_barrier
; #define PG8_STAGE(bufoff, gbase, voff) do { _Pragma("unroll") for (int _i = 0; _i < 2; ++_i) \
;         __builtin_amdgcn_global_load_lds((const unsigned*)((const char*)(gbase) + (voff)[_i]), (PG8_LAS unsigned*)(lds + (bufoff) + ldsw + _i * 8192), 16, 0, 0); } while (0)
; #define PG8_LDA(dst, b, h) do { _Pragma("unroll") for (int m = 0; m < 4; ++m) _Pragma("unroll") for (int k = 0; k < 2; ++k) dst[m][k] = *(const PG8_LAS bf16x8*)(lds + PG8_SA(b, h) + aoff + m * 2048 + k * 1024); } while (0)
; #define PG8_LDB(dst, b, h) do { _Pragma("unroll") for (int n = 0; n < 2; ++n) _Pragma("unroll") for (int k = 0; k < 2; ++k) dst[n][k] = *(const PG8_LAS bf16x8*)(lds + PG8_SB(b, h) + boff + n * 2048 + k * 1024); } while (0)
; #define PG8_MMA(ai, bj, At, Bt) do { __builtin_amdgcn_s_setprio(1); _Pragma("unroll") for (int m = 0; m < 4; ++m) _Pragma("unroll") for (int n = 0; n < 2; ++n) _Pragma("unroll") for (int k = 0; k < 2; ++k) \
;         acc[ai][bj][m][n] = __builtin_amdgcn_mfma_f32_16x16x32_bf16(Bt[n][k], At[m][k], acc[ai][bj][m][n], 0, 0, 0); __builtin_amdgcn_s_setprio(0); } while (0)
; #define PG8_WAIT_V(n) asm volatile("s_waitcnt vmcnt(" #n ")" ::: "memory")
; #define PG8_WAIT_L(n) asm volatile("s_waitcnt lgkmcnt(" #n ")" ::: "memory")
; #define PG8_BAR __builtin_amdgcn_s_barrier()
; #define PG8_SCHED __builtin_amdgcn_sched_barrier(0)
; template <class Epi, class Sched, bool ALIGN_EPI = false, bool SP2 = false>
; __device__ __forceinline__ void gemm_phase(PG8_LAS unsigned char* lds, const Gemm g, const Sched& S, const Epi& E) {
;     ...
;             PG8_WAIT_V(8); PG8_WAIT_L(0); PG8_BAR; PG8_MMA(1, 0, At, B0); PG8_MMA(1, 1, At, B1); PG8_BAR; PG8_SCHED;
;             PG8_LDB(B0, 1, 0); PG8_LDB(B1, 1, 1); PG8_SCHED; PG8_LDA(At, 1, 0); PG8_STAGE(PG8_SA(0, 1), a2 + hstepB, voffA);
;             PG8_WAIT_V(8); PG8_WAIT_L(0); PG8_BAR; PG8_MMA(0, 0, At, B0); PG8_MMA(0, 1, At, B1); PG8_BAR; PG8_SCHED;
	v_mfma_f32_16x16x32_bf16 v[60:63], v[128:131], v[186:189], v[60:63]
	v_mfma_f32_16x16x32_bf16 v[60:63], v[132:135], v[190:193], v[60:63]
	v_mfma_f32_16x16x32_bf16 v[56:59], v[136:139], v[186:189], v[56:59]
	v_mfma_f32_16x16x32_bf16 v[56:59], v[140:143], v[190:193], v[56:59]
	v_mfma_f32_16x16x32_bf16 v[44:47], v[128:131], v[194:197], v[44:47]
	v_mfma_f32_16x16x32_bf16 v[44:47], v[132:135], v[198:201], v[44:47]
	v_mfma_f32_16x16x32_bf16 v[40:43], v[136:139], v[194:197], v[40:43]
	v_mfma_f32_16x16x32_bf16 v[40:43], v[140:143], v[198:201], v[40:43]
	v_mfma_f32_16x16x32_bf16 v[28:31], v[128:131], v[202:205], v[28:31]
	v_mfma_f32_16x16x32_bf16 v[28:31], v[132:135], v[206:209], v[28:31]
	v_mfma_f32_16x16x32_bf16 v[24:27], v[136:139], v[202:205], v[24:27]
	v_mfma_f32_16x16x32_bf16 v[24:27], v[140:143], v[206:209], v[24:27]
	v_mfma_f32_16x16x32_bf16 v[12:15], v[128:131], v[210:213], v[12:15]
	v_mfma_f32_16x16x32_bf16 v[12:15], v[132:135], v[214:217], v[12:15]
	v_mfma_f32_16x16x32_bf16 v[8:11], v[136:139], v[210:213], v[8:11]
	v_mfma_f32_16x16x32_bf16 v[8:11], v[140:143], v[214:217], v[8:11]
	s_setprio 0
	s_setprio 1
	v_mfma_f32_16x16x32_bf16 v[52:55], v[144:147], v[186:189], v[52:55]
	v_mfma_f32_16x16x32_bf16 v[52:55], v[148:151], v[190:193], v[52:55]
	v_mfma_f32_16x16x32_bf16 v[48:51], v[178:181], v[186:189], v[48:51]
	v_mfma_f32_16x16x32_bf16 v[48:51], v[182:185], v[190:193], v[48:51]
	v_mfma_f32_16x16x32_bf16 v[36:39], v[144:147], v[194:197], v[36:39]
	v_mfma_f32_16x16x32_bf16 v[36:39], v[148:151], v[198:201], v[36:39]
	v_mfma_f32_16x16x32_bf16 v[32:35], v[178:181], v[194:197], v[32:35]
	v_mfma_f32_16x16x32_bf16 v[32:35], v[182:185], v[198:201], v[32:35]
	v_mfma_f32_16x16x32_bf16 v[20:23], v[144:147], v[202:205], v[20:23]
	v_mfma_f32_16x16x32_bf16 v[20:23], v[148:151], v[206:209], v[20:23]
	v_mfma_f32_16x16x32_bf16 v[16:19], v[178:181], v[202:205], v[16:19]
	v_mfma_f32_16x16x32_bf16 v[16:19], v[182:185], v[206:209], v[16:19]
	v_mfma_f32_16x16x32_bf16 v[4:7], v[144:147], v[210:213], v[4:7]
	v_mfma_f32_16x16x32_bf16 v[4:7], v[148:151], v[214:217], v[4:7]
	v_mfma_f32_16x16x32_bf16 v[0:3], v[178:181], v[210:213], v[0:3]
	v_mfma_f32_16x16x32_bf16 v[0:3], v[182:185], v[214:217], v[0:3]
	s_barrier
	s_setprio 0
	s_add_i32 s64, 0, 0x18000
	s_add_i32 s65, 0, 0x1c000
	v_add_u32_e32 v140, s64, v174
	v_add_u32_e32 v161, s65, v174
	ds_read_b128 v[128:131], v140
	ds_read_b128 v[132:135], v140 offset:1024
	ds_read_b128 v[136:139], v140 offset:2048
	ds_read_b128 v[140:143], v140 offset:3072
	ds_read_b128 v[144:147], v161
	ds_read_b128 v[148:151], v161 offset:1024
	ds_read_b128 v[178:181], v161 offset:2048
	ds_read_b128 v[182:185], v161 offset:3072
	s_add_u32 s42, s42, 0x4000
	s_addc_u32 s43, s43, 0
	s_mov_b32 m0, s23
	v_lshl_add_u64 v[172:173], s[42:43], 0, v[158:159]
	ds_read_b128 v[186:189], v177 offset:32768
	ds_read_b128 v[190:193], v177 offset:33792
	ds_read_b128 v[194:197], v177 offset:34816
	ds_read_b128 v[198:201], v177 offset:35840
	ds_read_b128 v[202:205], v177 offset:36864
	ds_read_b128 v[206:209], v177 offset:37888
	ds_read_b128 v[210:213], v177 offset:38912
	ds_read_b128 v[214:217], v177 offset:39936
	global_load_lds_dwordx4 v[172:173], off
	v_lshl_add_u64 v[172:173], s[42:43], 0, v[154:155]
	s_mov_b32 m0, s24
	s_nop 0
	global_load_lds_dwordx4 v[172:173], off
	s_setprio 1
	s_waitcnt vmcnt(8)
	s_waitcnt lgkmcnt(0)
	s_barrier
	v_mfma_f32_16x16x32_bf16 v[124:127], v[128:131], v[186:189], v[124:127]
	v_mfma_f32_16x16x32_bf16 v[124:127], v[132:135], v[190:193], v[124:127]
	v_mfma_f32_16x16x32_bf16 v[120:123], v[136:139], v[186:189], v[120:123]
	v_mfma_f32_16x16x32_bf16 v[120:123], v[140:143], v[190:193], v[120:123]
	v_mfma_f32_16x16x32_bf16 v[108:111], v[128:131], v[194:197], v[108:111]
	v_mfma_f32_16x16x32_bf16 v[108:111], v[132:135], v[198:201], v[108:111]
	v_mfma_f32_16x16x32_bf16 v[104:107], v[136:139], v[194:197], v[104:107]
	v_mfma_f32_16x16x32_bf16 v[104:107], v[140:143], v[198:201], v[104:107]
	v_mfma_f32_16x16x32_bf16 v[92:95], v[128:131], v[202:205], v[92:95]
	v_mfma_f32_16x16x32_bf16 v[92:95], v[132:135], v[206:209], v[92:95]
	v_mfma_f32_16x16x32_bf16 v[88:91], v[136:139], v[202:205], v[88:91]
	v_mfma_f32_16x16x32_bf16 v[88:91], v[140:143], v[206:209], v[88:91]
	v_mfma_f32_16x16x32_bf16 v[76:79], v[128:131], v[210:213], v[76:79]
	v_mfma_f32_16x16x32_bf16 v[76:79], v[132:135], v[214:217], v[76:79]
	v_mfma_f32_16x16x32_bf16 v[72:75], v[136:139], v[210:213], v[72:75]
	v_mfma_f32_16x16x32_bf16 v[72:75], v[140:143], v[214:217], v[72:75]
	s_setprio 0
	s_setprio 1
	v_mfma_f32_16x16x32_bf16 v[116:119], v[144:147], v[186:189], v[116:119]
	v_mfma_f32_16x16x32_bf16 v[116:119], v[148:151], v[190:193], v[116:119]
	v_mfma_f32_16x16x32_bf16 v[112:115], v[178:181], v[186:189], v[112:115]
	v_mfma_f32_16x16x32_bf16 v[112:115], v[182:185], v[190:193], v[112:115]
	v_mfma_f32_16x16x32_bf16 v[100:103], v[144:147], v[194:197], v[100:103]
	v_mfma_f32_16x16x32_bf16 v[100:103], v[148:151], v[198:201], v[100:103]
	v_mfma_f32_16x16x32_bf16 v[96:99], v[178:181], v[194:197], v[96:99]
	v_mfma_f32_16x16x32_bf16 v[96:99], v[182:185], v[198:201], v[96:99]
	v_mfma_f32_16x16x32_bf16 v[84:87], v[144:147], v[202:205], v[84:87]
	v_mfma_f32_16x16x32_bf16 v[84:87], v[148:151], v[206:209], v[84:87]
	v_mfma_f32_16x16x32_bf16 v[80:83], v[178:181], v[202:205], v[80:83]
	v_mfma_f32_16x16x32_bf16 v[80:83], v[182:185], v[206:209], v[80:83]
	v_mfma_f32_16x16x32_bf16 v[68:71], v[144:147], v[210:213], v[68:71]
	v_mfma_f32_16x16x32_bf16 v[68:71], v[148:151], v[214:217], v[68:71]
	v_mfma_f32_16x16x32_bf16 v[64:67], v[178:181], v[210:213], v[64:67]
	v_mfma_f32_16x16x32_bf16 v[64:67], v[182:185], v[214:217], v[64:67]
	s_barrier
; #define PG8_STAGE(bufoff, gbase, voff) do { _Pragma("unroll") for (int _i = 0; _i < 2; ++_i) \
;         __builtin_amdgcn_global_load_lds((const unsigned*)((const char*)(gbase) + (voff)[_i]), (PG8_LAS unsigned*)(lds + (bufoff) + ldsw + _i * 8192), 16, 0, 0); } while (0)
; #define PG8_LDA(dst, b, h) do { _Pragma("unroll") for (int m = 0; m < 4; ++m) _Pragma("unroll") for (int k = 0; k < 2; ++k) dst[m][k] = *(const PG8_LAS bf16x8*)(lds + PG8_SA(b, h) + aoff + m * 2048 + k * 1024); } while (0)
; #define PG8_MMA(ai, bj, At, Bt) do { __builtin_amdgcn_s_setprio(1); _Pragma("unroll") for (int m = 0; m < 4; ++m) _Pragma("unroll") for (int n = 0; n < 2; ++n) _Pragma("unroll") for (int k = 0; k < 2; ++k) \
;         acc[ai][bj][m][n] = __builtin_amdgcn_mfma_f32_16x16x32_bf16(Bt[n][k], At[m][k], acc[ai][bj][m][n], 0, 0, 0); __builtin_amdgcn_s_setprio(0); } while (0)
; #define PG8_WAIT_V(n) asm volatile("s_waitcnt vmcnt(" #n ")" ::: "memory")
; #define PG8_WAIT_L(n) asm volatile("s_waitcnt lgkmcnt(" #n ")" ::: "memory")
; #define PG8_BAR __builtin_amdgcn_s_barrier()
; #define PG8_SCHED __builtin_amdgcn_sched_barrier(0)
; template <class Epi, class Sched, bool ALIGN_EPI = false, bool SP2 = false>
; __device__ __forceinline__ void gemm_phase(PG8_LAS unsigned char* lds, const Gemm g, const Sched& S, const Epi& E) {
;     ...
;             PG8_LDA(At, 1, 1); PG8_STAGE(PG8_SB(1, 0), b3, voffB); PG8_STAGE(PG8_SB(1, 1), b3 + hstepB, voffB); PG8_STAGE(PG8_SA(1, 0), a3, voffA);
;             PG8_WAIT_V(8); PG8_WAIT_L(0); PG8_BAR; PG8_MMA(1, 0, At, B0); PG8_MMA(1, 1, At, B1); PG8_BAR; PG8_SCHED;
;     ...
;         if constexpr (ALIGN_EPI) { if (wr == 0) PG8_BAR; }
	s_setprio 0
	s_add_u32 s42, s40, 0x8000
	s_addc_u32 s43, s41, 0
	s_add_i32 s64, s64, s20
	v_lshl_add_u64 v[172:173], s[42:43], 0, v[156:157]
	s_mov_b32 m0, s64
	ds_read_b128 v[186:189], v177 offset:49152
	ds_read_b128 v[190:193], v177 offset:50176
	ds_read_b128 v[194:197], v177 offset:51200
	ds_read_b128 v[198:201], v177 offset:52224
	ds_read_b128 v[202:205], v177 offset:53248
	ds_read_b128 v[206:209], v177 offset:54272
	ds_read_b128 v[210:213], v177 offset:55296
	ds_read_b128 v[214:217], v177 offset:56320
	global_load_lds_dwordx4 v[172:173], off
	s_add_i32 m0, s64, 0x2000
	s_add_u32 s40, s40, 0xc000
	v_lshl_add_u64 v[172:173], s[42:43], 0, v[152:153]
	s_addc_u32 s41, s41, 0
	s_add_i32 s42, s65, s20
	global_load_lds_dwordx4 v[172:173], off
	v_lshl_add_u64 v[172:173], s[40:41], 0, v[156:157]
	s_mov_b32 m0, s42
	s_nop 0
	global_load_lds_dwordx4 v[172:173], off
	v_lshl_add_u64 v[172:173], s[40:41], 0, v[152:153]
	s_add_i32 m0, s42, 0x2000
	s_nop 0
	global_load_lds_dwordx4 v[172:173], off
	v_lshl_add_u64 v[172:173], s[38:39], 0, v[158:159]
	s_mov_b32 m0, s29
	s_nop 0
	global_load_lds_dwordx4 v[172:173], off
	v_lshl_add_u64 v[172:173], s[38:39], 0, v[154:155]
	s_mov_b32 m0, s30
	s_nop 0
	global_load_lds_dwordx4 v[172:173], off
	s_setprio 1
	s_waitcnt vmcnt(8)
	s_waitcnt lgkmcnt(0)
	s_barrier
	v_mfma_f32_16x16x32_bf16 v[60:63], v[128:131], v[186:189], v[60:63]
	v_mfma_f32_16x16x32_bf16 v[60:63], v[132:135], v[190:193], v[60:63]
	v_mfma_f32_16x16x32_bf16 v[56:59], v[136:139], v[186:189], v[56:59]
	v_mfma_f32_16x16x32_bf16 v[56:59], v[140:143], v[190:193], v[56:59]
	v_mfma_f32_16x16x32_bf16 v[44:47], v[128:131], v[194:197], v[44:47]
	v_mfma_f32_16x16x32_bf16 v[44:47], v[132:135], v[198:201], v[44:47]
	v_mfma_f32_16x16x32_bf16 v[40:43], v[136:139], v[194:197], v[40:43]
	v_mfma_f32_16x16x32_bf16 v[40:43], v[140:143], v[198:201], v[40:43]
	v_mfma_f32_16x16x32_bf16 v[28:31], v[128:131], v[202:205], v[28:31]
	v_mfma_f32_16x16x32_bf16 v[28:31], v[132:135], v[206:209], v[28:31]
	v_mfma_f32_16x16x32_bf16 v[24:27], v[136:139], v[202:205], v[24:27]
	v_mfma_f32_16x16x32_bf16 v[24:27], v[140:143], v[206:209], v[24:27]
	v_mfma_f32_16x16x32_bf16 v[12:15], v[128:131], v[210:213], v[12:15]
	v_mfma_f32_16x16x32_bf16 v[12:15], v[132:135], v[214:217], v[12:15]
	v_mfma_f32_16x16x32_bf16 v[8:11], v[136:139], v[210:213], v[8:11]
	v_mfma_f32_16x16x32_bf16 v[8:11], v[140:143], v[214:217], v[8:11]
	s_setprio 0
	s_setprio 1
	v_mfma_f32_16x16x32_bf16 v[52:55], v[144:147], v[186:189], v[52:55]
	v_mfma_f32_16x16x32_bf16 v[52:55], v[148:151], v[190:193], v[52:55]
	v_mfma_f32_16x16x32_bf16 v[48:51], v[178:181], v[186:189], v[48:51]
	v_mfma_f32_16x16x32_bf16 v[48:51], v[182:185], v[190:193], v[48:51]
	v_mfma_f32_16x16x32_bf16 v[36:39], v[144:147], v[194:197], v[36:39]
	v_mfma_f32_16x16x32_bf16 v[36:39], v[148:151], v[198:201], v[36:39]
	v_mfma_f32_16x16x32_bf16 v[32:35], v[178:181], v[194:197], v[32:35]
	v_mfma_f32_16x16x32_bf16 v[32:35], v[182:185], v[198:201], v[32:35]
	v_mfma_f32_16x16x32_bf16 v[20:23], v[144:147], v[202:205], v[20:23]
	v_mfma_f32_16x16x32_bf16 v[20:23], v[148:151], v[206:209], v[20:23]
	v_mfma_f32_16x16x32_bf16 v[16:19], v[178:181], v[202:205], v[16:19]
	v_mfma_f32_16x16x32_bf16 v[16:19], v[182:185], v[206:209], v[16:19]
	v_mfma_f32_16x16x32_bf16 v[4:7], v[144:147], v[210:213], v[4:7]
	v_mfma_f32_16x16x32_bf16 v[4:7], v[148:151], v[214:217], v[4:7]
	v_mfma_f32_16x16x32_bf16 v[0:3], v[178:181], v[210:213], v[0:3]
	v_mfma_f32_16x16x32_bf16 v[0:3], v[182:185], v[214:217], v[0:3]
	s_barrier
	s_setprio 0
	s_add_u32 s36, s36, 0x10000
	s_addc_u32 s37, s37, 0
	s_add_u32 s78, s78, 0x10000
	s_addc_u32 s82, s82, 0
	s_cmp_ge_u32 s84, s26
	s_mov_b32 s38, s84
	s_cbranch_scc0 .LBB0_193
	s_and_b64 vcc, exec, s[60:61]
	s_cbranch_vccz .LBB0_196
	s_barrier

; #define PG8_STAGE(bufoff, gbase, voff) do { _Pragma("unroll") for (int _i = 0; _i < 2; ++_i) \
;         __builtin_amdgcn_global_load_lds((const unsigned*)((const char*)(gbase) + (voff)[_i]), (PG8_LAS unsigned*)(lds + (bufoff) + ldsw + _i * 8192), 16, 0, 0); } while (0)
; #define PG8_LDA(dst, b, h) do { _Pragma("unroll") for (int m = 0; m < 4; ++m) _Pragma("unroll") for (int k = 0; k < 2; ++k) dst[m][k] = *(const PG8_LAS bf16x8*)(lds + PG8_SA(b, h) + aoff + m * 2048 + k * 1024); } while (0)
; #define PG8_LDB(dst, b, h) do { _Pragma("unroll") for (int n = 0; n < 2; ++n) _Pragma("unroll") for (int k = 0; k < 2; ++k) dst[n][k] = *(const PG8_LAS bf16x8*)(lds + PG8_SB(b, h) + boff + n * 2048 + k * 1024); } while (0)
; #define PG8_MMA(ai, bj, At, Bt) do { __builtin_amdgcn_s_setprio(1); _Pragma("unroll") for (int m = 0; m < 4; ++m) _Pragma("unroll") for (int n = 0; n < 2; ++n) _Pragma("unroll") for (int k = 0; k < 2; ++k) \
;         acc[ai][bj][m][n] = __builtin_amdgcn_mfma_f32_16x16x32_bf16(Bt[n][k], At[m][k], acc[ai][bj][m][n], 0, 0, 0); __builtin_amdgcn_s_setprio(0); } while (0)
; #define PG8_WAIT_V(n) asm volatile("s_waitcnt vmcnt(" #n ")" ::: "memory")
; #define PG8_WAIT_L(n) asm volatile("s_waitcnt lgkmcnt(" #n ")" ::: "memory")
; #define PG8_BAR __builtin_amdgcn_s_barrier()
; #define PG8_SCHED __builtin_amdgcn_sched_barrier(0)
; template <class Epi, class Sched, bool ALIGN_EPI = false, bool SP2 = false>
; __device__ __forceinline__ void gemm_phase(PG8_LAS unsigned char* lds, const Gemm g, const Sched& S, const Epi& E) {
;     ...
;         for (int t = 0; t < nt; t += 2) {
;             const bool last = (t == nt - 2);
;             const char* a1 = cA + (size_t)(t + 1) * kstepB;
;             const char* a2 = last ? nA : cA + (size_t)(t + 2) * kstepB; const char* b2 = last ? nB : cB + (size_t)(t + 2) * kstepB;
;             const char* a3 = a2 + kstepB; const char* b3 = b2 + kstepB;
;             if (last && has_next) S.a_ready(nxt);
;             if constexpr (SP2) {
;             PG8_LDB(B0, 0, 0); PG8_LDB(B1, 0, 1); PG8_SCHED; PG8_LDA(At, 0, 0); PG8_STAGE(PG8_SA(1, 1), a1 + hstepB, voffA);
;             PG8_WAIT_V(8); PG8_WAIT_L(0); PG8_BAR; PG8_MMA(0, 0, At, B0); PG8_MMA(0, 1, At, B1); PG8_BAR; PG8_SCHED;
;             PG8_LDA(At, 0, 1); PG8_STAGE(PG8_SB(0, 0), b2, voffB); PG8_STAGE(PG8_SB(0, 1), b2 + hstepB, voffB); PG8_STAGE(PG8_SA(0, 0), a2, voffA);
.LBB0_232:
	s_add_u32 s31, s36, 0x4000
	s_addc_u32 s38, s37, 0
	s_cmp_eq_u32 s30, 28
	s_cselect_b32 s42, s26, s31
	s_cselect_b32 s43, s13, s38
	s_cselect_b32 s40, s27, s28
	s_cselect_b32 s41, s11, s29
	s_add_u32 s38, s42, 0x8000
	s_addc_u32 s39, s43, 0
	s_add_i32 s31, 0, 0x10000
	s_add_i32 s60, 0, 0x14000
	v_add_u32_e32 v152, s31, v169
	v_add_u32_e32 v175, s60, v169
	ds_read_b128 v[128:131], v152
	ds_read_b128 v[132:135], v152 offset:1024
	ds_read_b128 v[148:151], v152 offset:2048
	ds_read_b128 v[152:155], v152 offset:3072
	ds_read_b128 v[156:159], v175
	ds_read_b128 v[160:163], v175 offset:1024
	ds_read_b128 v[164:167], v175 offset:2048
	ds_read_b128 v[176:179], v175 offset:3072
	v_lshl_add_u64 v[212:213], s[36:37], 0, v[144:145]
	s_add_i32 m0, s17, 0xc000
	ds_read_b128 v[180:183], v174
	ds_read_b128 v[184:187], v174 offset:1024
	ds_read_b128 v[188:191], v174 offset:2048
	ds_read_b128 v[192:195], v174 offset:3072
	ds_read_b128 v[196:199], v174 offset:4096
	ds_read_b128 v[200:203], v174 offset:5120
	ds_read_b128 v[204:207], v174 offset:6144
	ds_read_b128 v[208:211], v174 offset:7168
	global_load_lds_dwordx4 v[212:213], off
	v_lshl_add_u64 v[212:213], s[36:37], 0, v[146:147]
	s_add_i32 m0, s17, 0xe000
	s_nop 0
	global_load_lds_dwordx4 v[212:213], off
	s_setprio 1
	s_waitcnt vmcnt(8)
	s_waitcnt lgkmcnt(0)
	s_barrier
	v_mfma_f32_16x16x32_bf16 v[124:127], v[128:131], v[180:183], v[124:127]
	v_mfma_f32_16x16x32_bf16 v[124:127], v[132:135], v[184:187], v[124:127]
	v_mfma_f32_16x16x32_bf16 v[120:123], v[148:151], v[180:183], v[120:123]
	v_mfma_f32_16x16x32_bf16 v[120:123], v[152:155], v[184:187], v[120:123]
	v_mfma_f32_16x16x32_bf16 v[108:111], v[128:131], v[188:191], v[108:111]
	v_mfma_f32_16x16x32_bf16 v[108:111], v[132:135], v[192:195], v[108:111]
	v_mfma_f32_16x16x32_bf16 v[104:107], v[148:151], v[188:191], v[104:107]
	v_mfma_f32_16x16x32_bf16 v[104:107], v[152:155], v[192:195], v[104:107]
	v_mfma_f32_16x16x32_bf16 v[92:95], v[128:131], v[196:199], v[92:95]
	v_mfma_f32_16x16x32_bf16 v[92:95], v[132:135], v[200:203], v[92:95]
	v_mfma_f32_16x16x32_bf16 v[88:91], v[148:151], v[196:199], v[88:91]
	v_mfma_f32_16x16x32_bf16 v[88:91], v[152:155], v[200:203], v[88:91]
	v_mfma_f32_16x16x32_bf16 v[76:79], v[128:131], v[204:207], v[76:79]
	v_mfma_f32_16x16x32_bf16 v[76:79], v[132:135], v[208:211], v[76:79]
	v_mfma_f32_16x16x32_bf16 v[72:75], v[148:151], v[204:207], v[72:75]
	v_mfma_f32_16x16x32_bf16 v[72:75], v[152:155], v[208:211], v[72:75]
	s_setprio 0
	s_setprio 1
	v_mfma_f32_16x16x32_bf16 v[116:119], v[156:159], v[180:183], v[116:119]
	v_mfma_f32_16x16x32_bf16 v[116:119], v[160:163], v[184:187], v[116:119]
	v_mfma_f32_16x16x32_bf16 v[112:115], v[164:167], v[180:183], v[112:115]
	v_mfma_f32_16x16x32_bf16 v[112:115], v[176:179], v[184:187], v[112:115]
	v_mfma_f32_16x16x32_bf16 v[100:103], v[156:159], v[188:191], v[100:103]
	v_mfma_f32_16x16x32_bf16 v[100:103], v[160:163], v[192:195], v[100:103]
	v_mfma_f32_16x16x32_bf16 v[96:99], v[164:167], v[188:191], v[96:99]
	v_mfma_f32_16x16x32_bf16 v[96:99], v[176:179], v[192:195], v[96:99]
	v_mfma_f32_16x16x32_bf16 v[84:87], v[156:159], v[196:199], v[84:87]
	v_mfma_f32_16x16x32_bf16 v[84:87], v[160:163], v[200:203], v[84:87]
	v_mfma_f32_16x16x32_bf16 v[80:83], v[164:167], v[196:199], v[80:83]
	v_mfma_f32_16x16x32_bf16 v[80:83], v[176:179], v[200:203], v[80:83]
	v_mfma_f32_16x16x32_bf16 v[68:71], v[156:159], v[204:207], v[68:71]
	v_mfma_f32_16x16x32_bf16 v[68:71], v[160:163], v[208:211], v[68:71]
	v_mfma_f32_16x16x32_bf16 v[64:67], v[164:167], v[204:207], v[64:67]
	v_mfma_f32_16x16x32_bf16 v[64:67], v[176:179], v[208:211], v[64:67]
	s_barrier
	s_setprio 0
	s_add_i32 s31, s31, s14
	v_lshl_add_u64 v[212:213], s[40:41], 0, v[220:221]
	s_mov_b32 m0, s31
	ds_read_b128 v[180:183], v174 offset:16384
	ds_read_b128 v[184:187], v174 offset:17408
	ds_read_b128 v[188:191], v174 offset:18432
	ds_read_b128 v[192:195], v174 offset:19456
	ds_read_b128 v[196:199], v174 offset:20480
	ds_read_b128 v[200:203], v174 offset:21504
	ds_read_b128 v[204:207], v174 offset:22528
	ds_read_b128 v[208:211], v174 offset:23552
	global_load_lds_dwordx4 v[212:213], off
	s_add_i32 m0, s31, 0x2000
	s_add_u32 s44, s40, 0x4000
	v_lshl_add_u64 v[212:213], s[40:41], 0, v[136:137]
	s_addc_u32 s45, s41, 0
	s_add_i32 s31, s60, s14
	global_load_lds_dwordx4 v[212:213], off
	v_lshl_add_u64 v[212:213], s[44:45], 0, v[220:221]
	s_mov_b32 m0, s31
	s_nop 0
	global_load_lds_dwordx4 v[212:213], off
	v_lshl_add_u64 v[212:213], s[44:45], 0, v[136:137]
	s_add_i32 m0, s31, 0x2000
	s_nop 0
	global_load_lds_dwordx4 v[212:213], off
	v_lshl_add_u64 v[212:213], s[42:43], 0, v[140:141]
	s_mov_b32 m0, s17
	s_nop 0
	global_load_lds_dwordx4 v[212:213], off
	v_lshl_add_u64 v[212:213], s[42:43], 0, v[138:139]
	s_mov_b32 m0, s18
	s_nop 0
	global_load_lds_dwordx4 v[212:213], off
	s_setprio 1
	s_waitcnt vmcnt(8)
	s_waitcnt lgkmcnt(0)
	s_barrier
; #define PG8_STAGE(bufoff, gbase, voff) do { _Pragma("unroll") for (int _i = 0; _i < 2; ++_i) \
;         __builtin_amdgcn_global_load_lds((const unsigned*)((const char*)(gbase) + (voff)[_i]), (PG8_LAS unsigned*)(lds + (bufoff) + ldsw + _i * 8192), 16, 0, 0); } while (0)
; #define PG8_LDA(dst, b, h) do { _Pragma("unroll") for (int m = 0; m < 4; ++m) _Pragma("unroll") for (int k = 0; k < 2; ++k) dst[m][k] = *(const PG8_LAS bf16x8*)(lds + PG8_SA(b, h) + aoff + m * 2048 + k * 1024); } while (0)
; #define PG8_LDB(dst, b, h) do { _Pragma("unroll") for (int n = 0; n < 2; ++n) _Pragma("unroll") for (int k = 0; k < 2; ++k) dst[n][k] = *(const PG8_LAS bf16x8*)(lds + PG8_SB(b, h) + boff + n * 2048 + k * 1024); } while (0)
; #define PG8_MMA(ai, bj, At, Bt) do { __builtin_amdgcn_s_setprio(1); _Pragma("unroll") for (int m = 0; m < 4; ++m) _Pragma("unroll") for (int n = 0; n < 2; ++n) _Pragma("unroll") for (int k = 0; k < 2; ++k) \
;         acc[ai][bj][m][n] = __builtin_amdgcn_mfma_f32_16x16x32_bf16(Bt[n][k], At[m][k], acc[ai][bj][m][n], 0, 0, 0); __builtin_amdgcn_s_setprio(0); } while (0)
; #define PG8_WAIT_V(n) asm volatile("s_waitcnt vmcnt(" #n ")" ::: "memory")
; #define PG8_WAIT_L(n) asm volatile("s_waitcnt lgkmcnt(" #n ")" ::: "memory")
; #define PG8_BAR __builtin_amdgcn_s_barrier()
; #define PG8_SCHED __builtin_amdgcn_sched_barrier(0)
; template <class Epi, class Sched, bool ALIGN_EPI = false, bool SP2 = false>
; __device__ __forceinline__ void gemm_phase(PG8_LAS unsigned char* lds, const Gemm g, const Sched& S, const Epi& E) {
;     ...
;             PG8_WAIT_V(8); PG8_WAIT_L(0); PG8_BAR; PG8_MMA(1, 0, At, B0); PG8_MMA(1, 1, At, B1); PG8_BAR; PG8_SCHED;
;             PG8_LDB(B0, 1, 0); PG8_LDB(B1, 1, 1); PG8_SCHED; PG8_LDA(At, 1, 0); PG8_STAGE(PG8_SA(0, 1), a2 + hstepB, voffA);
;             PG8_WAIT_V(8); PG8_WAIT_L(0); PG8_BAR; PG8_MMA(0, 0, At, B0); PG8_MMA(0, 1, At, B1); PG8_BAR; PG8_SCHED;
	v_mfma_f32_16x16x32_bf16 v[60:63], v[128:131], v[180:183], v[60:63]
	v_mfma_f32_16x16x32_bf16 v[60:63], v[132:135], v[184:187], v[60:63]
	v_mfma_f32_16x16x32_bf16 v[56:59], v[148:151], v[180:183], v[56:59]
	v_mfma_f32_16x16x32_bf16 v[56:59], v[152:155], v[184:187], v[56:59]
	v_mfma_f32_16x16x32_bf16 v[48:51], v[128:131], v[188:191], v[48:51]
	v_mfma_f32_16x16x32_bf16 v[48:51], v[132:135], v[192:195], v[48:51]
	v_mfma_f32_16x16x32_bf16 v[40:43], v[148:151], v[188:191], v[40:43]
	v_mfma_f32_16x16x32_bf16 v[40:43], v[152:155], v[192:195], v[40:43]
	v_mfma_f32_16x16x32_bf16 v[32:35], v[128:131], v[196:199], v[32:35]
	v_mfma_f32_16x16x32_bf16 v[32:35], v[132:135], v[200:203], v[32:35]
	v_mfma_f32_16x16x32_bf16 v[24:27], v[148:151], v[196:199], v[24:27]
	v_mfma_f32_16x16x32_bf16 v[24:27], v[152:155], v[200:203], v[24:27]
	v_mfma_f32_16x16x32_bf16 v[16:19], v[128:131], v[204:207], v[16:19]
	v_mfma_f32_16x16x32_bf16 v[16:19], v[132:135], v[208:211], v[16:19]
	v_mfma_f32_16x16x32_bf16 v[8:11], v[148:151], v[204:207], v[8:11]
	v_mfma_f32_16x16x32_bf16 v[8:11], v[152:155], v[208:211], v[8:11]
	s_setprio 0
	s_setprio 1
	v_mfma_f32_16x16x32_bf16 v[52:55], v[156:159], v[180:183], v[52:55]
	v_mfma_f32_16x16x32_bf16 v[52:55], v[160:163], v[184:187], v[52:55]
	v_mfma_f32_16x16x32_bf16 v[44:47], v[164:167], v[180:183], v[44:47]
	v_mfma_f32_16x16x32_bf16 v[44:47], v[176:179], v[184:187], v[44:47]
	v_mfma_f32_16x16x32_bf16 v[36:39], v[156:159], v[188:191], v[36:39]
	v_mfma_f32_16x16x32_bf16 v[36:39], v[160:163], v[192:195], v[36:39]
	v_mfma_f32_16x16x32_bf16 v[28:31], v[164:167], v[188:191], v[28:31]
	v_mfma_f32_16x16x32_bf16 v[28:31], v[176:179], v[192:195], v[28:31]
	v_mfma_f32_16x16x32_bf16 v[20:23], v[156:159], v[196:199], v[20:23]
	v_mfma_f32_16x16x32_bf16 v[20:23], v[160:163], v[200:203], v[20:23]
	v_mfma_f32_16x16x32_bf16 v[12:15], v[164:167], v[196:199], v[12:15]
	v_mfma_f32_16x16x32_bf16 v[12:15], v[176:179], v[200:203], v[12:15]
	v_mfma_f32_16x16x32_bf16 v[4:7], v[156:159], v[204:207], v[4:7]
	v_mfma_f32_16x16x32_bf16 v[4:7], v[160:163], v[208:211], v[4:7]
	v_mfma_f32_16x16x32_bf16 v[0:3], v[164:167], v[204:207], v[0:3]
	v_mfma_f32_16x16x32_bf16 v[0:3], v[176:179], v[208:211], v[0:3]
	s_barrier
	s_setprio 0
	s_add_i32 s31, 0, 0x18000
	s_add_i32 s44, 0, 0x1c000
	v_add_u32_e32 v152, s31, v169
	v_add_u32_e32 v175, s44, v169
	ds_read_b128 v[128:131], v152
	ds_read_b128 v[132:135], v152 offset:1024
	ds_read_b128 v[148:151], v152 offset:2048
	ds_read_b128 v[152:155], v152 offset:3072
	ds_read_b128 v[156:159], v175
	ds_read_b128 v[160:163], v175 offset:1024
	ds_read_b128 v[164:167], v175 offset:2048
	ds_read_b128 v[176:179], v175 offset:3072
	s_add_u32 s42, s42, 0x4000
	s_addc_u32 s43, s43, 0
	s_mov_b32 m0, s19
	v_lshl_add_u64 v[212:213], s[42:43], 0, v[140:141]
	ds_read_b128 v[180:183], v174 offset:32768
	ds_read_b128 v[184:187], v174 offset:33792
	ds_read_b128 v[188:191], v174 offset:34816
	ds_read_b128 v[192:195], v174 offset:35840
	ds_read_b128 v[196:199], v174 offset:36864
	ds_read_b128 v[200:203], v174 offset:37888
	ds_read_b128 v[204:207], v174 offset:38912
	ds_read_b128 v[208:211], v174 offset:39936
	global_load_lds_dwordx4 v[212:213], off
	v_lshl_add_u64 v[212:213], s[42:43], 0, v[138:139]
	s_mov_b32 m0, s20
	s_nop 0
	global_load_lds_dwordx4 v[212:213], off
	s_setprio 1
	s_waitcnt vmcnt(8)
	s_waitcnt lgkmcnt(0)
	s_barrier
	v_mfma_f32_16x16x32_bf16 v[124:127], v[128:131], v[180:183], v[124:127]
	v_mfma_f32_16x16x32_bf16 v[124:127], v[132:135], v[184:187], v[124:127]
	v_mfma_f32_16x16x32_bf16 v[120:123], v[148:151], v[180:183], v[120:123]
	v_mfma_f32_16x16x32_bf16 v[120:123], v[152:155], v[184:187], v[120:123]
	v_mfma_f32_16x16x32_bf16 v[108:111], v[128:131], v[188:191], v[108:111]
	v_mfma_f32_16x16x32_bf16 v[108:111], v[132:135], v[192:195], v[108:111]
	v_mfma_f32_16x16x32_bf16 v[104:107], v[148:151], v[188:191], v[104:107]
	v_mfma_f32_16x16x32_bf16 v[104:107], v[152:155], v[192:195], v[104:107]
	v_mfma_f32_16x16x32_bf16 v[92:95], v[128:131], v[196:199], v[92:95]
	v_mfma_f32_16x16x32_bf16 v[92:95], v[132:135], v[200:203], v[92:95]
	v_mfma_f32_16x16x32_bf16 v[88:91], v[148:151], v[196:199], v[88:91]
	v_mfma_f32_16x16x32_bf16 v[88:91], v[152:155], v[200:203], v[88:91]
	v_mfma_f32_16x16x32_bf16 v[76:79], v[128:131], v[204:207], v[76:79]
	v_mfma_f32_16x16x32_bf16 v[76:79], v[132:135], v[208:211], v[76:79]
	v_mfma_f32_16x16x32_bf16 v[72:75], v[148:151], v[204:207], v[72:75]
	v_mfma_f32_16x16x32_bf16 v[72:75], v[152:155], v[208:211], v[72:75]
	s_setprio 0
	s_setprio 1
	v_mfma_f32_16x16x32_bf16 v[116:119], v[156:159], v[180:183], v[116:119]
	v_mfma_f32_16x16x32_bf16 v[116:119], v[160:163], v[184:187], v[116:119]
	v_mfma_f32_16x16x32_bf16 v[112:115], v[164:167], v[180:183], v[112:115]
	v_mfma_f32_16x16x32_bf16 v[112:115], v[176:179], v[184:187], v[112:115]
	v_mfma_f32_16x16x32_bf16 v[100:103], v[156:159], v[188:191], v[100:103]
	v_mfma_f32_16x16x32_bf16 v[100:103], v[160:163], v[192:195], v[100:103]
	v_mfma_f32_16x16x32_bf16 v[96:99], v[164:167], v[188:191], v[96:99]
	v_mfma_f32_16x16x32_bf16 v[96:99], v[176:179], v[192:195], v[96:99]
	v_mfma_f32_16x16x32_bf16 v[84:87], v[156:159], v[196:199], v[84:87]
	v_mfma_f32_16x16x32_bf16 v[84:87], v[160:163], v[200:203], v[84:87]
	v_mfma_f32_16x16x32_bf16 v[80:83], v[164:167], v[196:199], v[80:83]
	v_mfma_f32_16x16x32_bf16 v[80:83], v[176:179], v[200:203], v[80:83]
	v_mfma_f32_16x16x32_bf16 v[68:71], v[156:159], v[204:207], v[68:71]
	v_mfma_f32_16x16x32_bf16 v[68:71], v[160:163], v[208:211], v[68:71]
	v_mfma_f32_16x16x32_bf16 v[64:67], v[164:167], v[204:207], v[64:67]
	v_mfma_f32_16x16x32_bf16 v[64:67], v[176:179], v[208:211], v[64:67]
	s_barrier
; #define PG8_STAGE(bufoff, gbase, voff) do { _Pragma("unroll") for (int _i = 0; _i < 2; ++_i) \
;         __builtin_amdgcn_global_load_lds((const unsigned*)((const char*)(gbase) + (voff)[_i]), (PG8_LAS unsigned*)(lds + (bufoff) + ldsw + _i * 8192), 16, 0, 0); } while (0)
; #define PG8_LDA(dst, b, h) do { _Pragma("unroll") for (int m = 0; m < 4; ++m) _Pragma("unroll") for (int k = 0; k < 2; ++k) dst[m][k] = *(const PG8_LAS bf16x8*)(lds + PG8_SA(b, h) + aoff + m * 2048 + k * 1024); } while (0)
; #define PG8_MMA(ai, bj, At, Bt) do { __builtin_amdgcn_s_setprio(1); _Pragma("unroll") for (int m = 0; m < 4; ++m) _Pragma("unroll") for (int n = 0; n < 2; ++n) _Pragma("unroll") for (int k = 0; k < 2; ++k) \
;         acc[ai][bj][m][n] = __builtin_amdgcn_mfma_f32_16x16x32_bf16(Bt[n][k], At[m][k], acc[ai][bj][m][n], 0, 0, 0); __builtin_amdgcn_s_setprio(0); } while (0)
; #define PG8_WAIT_V(n) asm volatile("s_waitcnt vmcnt(" #n ")" ::: "memory")
; #define PG8_WAIT_L(n) asm volatile("s_waitcnt lgkmcnt(" #n ")" ::: "memory")
; #define PG8_BAR __builtin_amdgcn_s_barrier()
; #define PG8_SCHED __builtin_amdgcn_sched_barrier(0)
; template <class Epi, class Sched, bool ALIGN_EPI = false, bool SP2 = false>
; __device__ __forceinline__ void gemm_phase(PG8_LAS unsigned char* lds, const Gemm g, const Sched& S, const Epi& E) {
;     ...
;             PG8_LDA(At, 1, 1); PG8_STAGE(PG8_SB(1, 0), b3, voffB); PG8_STAGE(PG8_SB(1, 1), b3 + hstepB, voffB); PG8_STAGE(PG8_SA(1, 0), a3, voffA);
;             PG8_WAIT_V(8); PG8_WAIT_L(0); PG8_BAR; PG8_MMA(1, 0, At, B0); PG8_MMA(1, 1, At, B1); PG8_BAR; PG8_SCHED;
;     ...
;         if constexpr (ALIGN_EPI) { if (wr == 0) PG8_BAR; }
	s_setprio 0
	s_add_u32 s42, s40, 0x8000
	s_addc_u32 s43, s41, 0
	s_add_i32 s31, s31, s14
	v_lshl_add_u64 v[212:213], s[42:43], 0, v[220:221]
	s_mov_b32 m0, s31
	ds_read_b128 v[180:183], v174 offset:49152
	ds_read_b128 v[184:187], v174 offset:50176
	ds_read_b128 v[188:191], v174 offset:51200
	ds_read_b128 v[192:195], v174 offset:52224
	ds_read_b128 v[196:199], v174 offset:53248
	ds_read_b128 v[200:203], v174 offset:54272
	ds_read_b128 v[204:207], v174 offset:55296
	ds_read_b128 v[208:211], v174 offset:56320
	global_load_lds_dwordx4 v[212:213], off
	s_add_i32 m0, s31, 0x2000
	s_add_u32 s40, s40, 0xc000
	v_lshl_add_u64 v[212:213], s[42:43], 0, v[136:137]
	s_addc_u32 s41, s41, 0
	s_add_i32 s31, s44, s14
	global_load_lds_dwordx4 v[212:213], off
	v_lshl_add_u64 v[212:213], s[40:41], 0, v[220:221]
	s_mov_b32 m0, s31
	s_nop 0
	global_load_lds_dwordx4 v[212:213], off
	v_lshl_add_u64 v[212:213], s[40:41], 0, v[136:137]
	s_add_i32 m0, s31, 0x2000
	s_nop 0
	global_load_lds_dwordx4 v[212:213], off
	v_lshl_add_u64 v[212:213], s[38:39], 0, v[140:141]
	s_mov_b32 m0, s21
	s_nop 0
	global_load_lds_dwordx4 v[212:213], off
	v_lshl_add_u64 v[212:213], s[38:39], 0, v[138:139]
	s_mov_b32 m0, s22
	s_nop 0
	global_load_lds_dwordx4 v[212:213], off
	s_setprio 1
	s_waitcnt vmcnt(8)
	s_waitcnt lgkmcnt(0)
	s_barrier
	v_mfma_f32_16x16x32_bf16 v[60:63], v[128:131], v[180:183], v[60:63]
	v_mfma_f32_16x16x32_bf16 v[60:63], v[132:135], v[184:187], v[60:63]
	v_mfma_f32_16x16x32_bf16 v[56:59], v[148:151], v[180:183], v[56:59]
	v_mfma_f32_16x16x32_bf16 v[56:59], v[152:155], v[184:187], v[56:59]
	v_mfma_f32_16x16x32_bf16 v[48:51], v[128:131], v[188:191], v[48:51]
	v_mfma_f32_16x16x32_bf16 v[48:51], v[132:135], v[192:195], v[48:51]
	v_mfma_f32_16x16x32_bf16 v[40:43], v[148:151], v[188:191], v[40:43]
	v_mfma_f32_16x16x32_bf16 v[40:43], v[152:155], v[192:195], v[40:43]
	v_mfma_f32_16x16x32_bf16 v[32:35], v[128:131], v[196:199], v[32:35]
	v_mfma_f32_16x16x32_bf16 v[32:35], v[132:135], v[200:203], v[32:35]
	v_mfma_f32_16x16x32_bf16 v[24:27], v[148:151], v[196:199], v[24:27]
	v_mfma_f32_16x16x32_bf16 v[24:27], v[152:155], v[200:203], v[24:27]
	v_mfma_f32_16x16x32_bf16 v[16:19], v[128:131], v[204:207], v[16:19]
	v_mfma_f32_16x16x32_bf16 v[16:19], v[132:135], v[208:211], v[16:19]
	v_mfma_f32_16x16x32_bf16 v[8:11], v[148:151], v[204:207], v[8:11]
	v_mfma_f32_16x16x32_bf16 v[8:11], v[152:155], v[208:211], v[8:11]
	s_setprio 0
	s_setprio 1
	v_mfma_f32_16x16x32_bf16 v[52:55], v[156:159], v[180:183], v[52:55]
	v_mfma_f32_16x16x32_bf16 v[52:55], v[160:163], v[184:187], v[52:55]
	v_mfma_f32_16x16x32_bf16 v[44:47], v[164:167], v[180:183], v[44:47]
	v_mfma_f32_16x16x32_bf16 v[44:47], v[176:179], v[184:187], v[44:47]
	v_mfma_f32_16x16x32_bf16 v[36:39], v[156:159], v[188:191], v[36:39]
	v_mfma_f32_16x16x32_bf16 v[36:39], v[160:163], v[192:195], v[36:39]
	v_mfma_f32_16x16x32_bf16 v[28:31], v[164:167], v[188:191], v[28:31]
	v_mfma_f32_16x16x32_bf16 v[28:31], v[176:179], v[192:195], v[28:31]
	v_mfma_f32_16x16x32_bf16 v[20:23], v[156:159], v[196:199], v[20:23]
	v_mfma_f32_16x16x32_bf16 v[20:23], v[160:163], v[200:203], v[20:23]
	v_mfma_f32_16x16x32_bf16 v[12:15], v[164:167], v[196:199], v[12:15]
	v_mfma_f32_16x16x32_bf16 v[12:15], v[176:179], v[200:203], v[12:15]
	v_mfma_f32_16x16x32_bf16 v[4:7], v[156:159], v[204:207], v[4:7]
	v_mfma_f32_16x16x32_bf16 v[4:7], v[160:163], v[208:211], v[4:7]
	v_mfma_f32_16x16x32_bf16 v[0:3], v[164:167], v[204:207], v[0:3]
	v_mfma_f32_16x16x32_bf16 v[0:3], v[176:179], v[208:211], v[0:3]
	s_barrier
	s_setprio 0
	s_add_i32 s30, s30, 2
	s_add_u32 s36, s36, 0x10000
	s_addc_u32 s37, s37, 0
	s_add_u32 s28, s28, 0x10000
	s_addc_u32 s29, s29, 0
	s_cmp_gt_u32 s30, 29
	s_cbranch_scc0 .LBB0_232
	s_and_b64 vcc, exec, s[8:9]
	s_cbranch_vccz .LBB0_235
	s_barrier

; #define PG8_STAGE(bufoff, gbase, voff) do { _Pragma("unroll") for (int _i = 0; _i < 2; ++_i) \
;         __builtin_amdgcn_global_load_lds((const unsigned*)((const char*)(gbase) + (voff)[_i]), (PG8_LAS unsigned*)(lds + (bufoff) + ldsw + _i * 8192), 16, 0, 0); } while (0)
; #define PG8_LDA(dst, b, h) do { _Pragma("unroll") for (int m = 0; m < 4; ++m) _Pragma("unroll") for (int k = 0; k < 2; ++k) dst[m][k] = *(const PG8_LAS bf16x8*)(lds + PG8_SA(b, h) + aoff + m * 2048 + k * 1024); } while (0)
; #define PG8_LDB(dst, b, h) do { _Pragma("unroll") for (int n = 0; n < 2; ++n) _Pragma("unroll") for (int k = 0; k < 2; ++k) dst[n][k] = *(const PG8_LAS bf16x8*)(lds + PG8_SB(b, h) + boff + n * 2048 + k * 1024); } while (0)
; #define PG8_MMA(ai, bj, At, Bt) do { __builtin_amdgcn_s_setprio(1); _Pragma("unroll") for (int m = 0; m < 4; ++m) _Pragma("unroll") for (int n = 0; n < 2; ++n) _Pragma("unroll") for (int k = 0; k < 2; ++k) \
;         acc[ai][bj][m][n] = __builtin_amdgcn_mfma_f32_16x16x32_bf16(Bt[n][k], At[m][k], acc[ai][bj][m][n], 0, 0, 0); __builtin_amdgcn_s_setprio(0); } while (0)
; #define PG8_WAIT_V(n) asm volatile("s_waitcnt vmcnt(" #n ")" ::: "memory")
; #define PG8_WAIT_L(n) asm volatile("s_waitcnt lgkmcnt(" #n ")" ::: "memory")
; #define PG8_BAR __builtin_amdgcn_s_barrier()
; #define PG8_SCHED __builtin_amdgcn_sched_barrier(0)
; template <class Epi, class Sched, bool ALIGN_EPI = false, bool SP2 = false>
; __device__ __forceinline__ void gemm_phase(PG8_LAS unsigned char* lds, const Gemm g, const Sched& S, const Epi& E) {
;     ...
;         for (int t = 0; t < nt; t += 2) {
;             const bool last = (t == nt - 2);
;             const char* a1 = cA + (size_t)(t + 1) * kstepB;
;             const char* a2 = last ? nA : cA + (size_t)(t + 2) * kstepB; const char* b2 = last ? nB : cB + (size_t)(t + 2) * kstepB;
;             const char* a3 = a2 + kstepB; const char* b3 = b2 + kstepB;
;             if (last && has_next) S.a_ready(nxt);
;             if constexpr (SP2) {
;             PG8_LDB(B0, 0, 0); PG8_LDB(B1, 0, 1); PG8_SCHED; PG8_LDA(At, 0, 0); PG8_STAGE(PG8_SA(1, 1), a1 + hstepB, voffA);
;             PG8_WAIT_V(8); PG8_WAIT_L(0); PG8_BAR; PG8_MMA(0, 0, At, B0); PG8_MMA(0, 1, At, B1); PG8_BAR; PG8_SCHED;
;             PG8_LDA(At, 0, 1); PG8_STAGE(PG8_SB(0, 0), b2, voffB); PG8_STAGE(PG8_SB(0, 1), b2 + hstepB, voffB); PG8_STAGE(PG8_SA(0, 0), a2, voffA);
.LBB0_263:
	s_add_u32 s38, s36, 0x4000
	s_addc_u32 s39, s37, 0
	s_cmp_eq_u32 s62, 28
	s_cselect_b32 s42, s30, s38
	s_cselect_b32 s43, s13, s39
	s_cselect_b32 s40, s31, s44
	s_cselect_b32 s41, s11, s45
	s_add_u32 s38, s42, 0x8000
	s_addc_u32 s39, s43, 0
	s_add_i32 s63, 0, 0x10000
	v_add_u32_e32 v151, s63, v165
	s_add_i32 s75, 0, 0x14000
	ds_read_b128 v[128:131], v151
	ds_read_b128 v[132:135], v151 offset:1024
	ds_read_b128 v[152:155], v151 offset:2048
	ds_read_b128 v[156:159], v151 offset:3072
	v_add_u32_e32 v151, s75, v165
	ds_read_b128 v[160:163], v151
	ds_read_b128 v[170:173], v151 offset:1024
	ds_read_b128 v[174:177], v151 offset:2048
	ds_read_b128 v[178:181], v151 offset:3072
	v_lshl_add_u64 v[214:215], s[36:37], 0, v[146:147]
	s_add_i32 m0, s19, 0xc000
	ds_read_b128 v[182:185], v168
	ds_read_b128 v[186:189], v168 offset:1024
	ds_read_b128 v[190:193], v168 offset:2048
	ds_read_b128 v[194:197], v168 offset:3072
	ds_read_b128 v[198:201], v168 offset:4096
	ds_read_b128 v[202:205], v168 offset:5120
	ds_read_b128 v[206:209], v168 offset:6144
	ds_read_b128 v[210:213], v168 offset:7168
	global_load_lds_dwordx4 v[214:215], off
	v_lshl_add_u64 v[214:215], s[36:37], 0, v[148:149]
	s_add_i32 m0, s19, 0xe000
	s_nop 0
	global_load_lds_dwordx4 v[214:215], off
	s_setprio 1
	s_waitcnt vmcnt(8)
	s_waitcnt lgkmcnt(0)
	s_barrier
	v_mfma_f32_16x16x32_bf16 v[124:127], v[128:131], v[182:185], v[124:127]
	v_mfma_f32_16x16x32_bf16 v[124:127], v[132:135], v[186:189], v[124:127]
	v_mfma_f32_16x16x32_bf16 v[116:119], v[152:155], v[182:185], v[116:119]
	v_mfma_f32_16x16x32_bf16 v[116:119], v[156:159], v[186:189], v[116:119]
	v_mfma_f32_16x16x32_bf16 v[108:111], v[128:131], v[190:193], v[108:111]
	v_mfma_f32_16x16x32_bf16 v[108:111], v[132:135], v[194:197], v[108:111]
	v_mfma_f32_16x16x32_bf16 v[100:103], v[152:155], v[190:193], v[100:103]
	v_mfma_f32_16x16x32_bf16 v[100:103], v[156:159], v[194:197], v[100:103]
	v_mfma_f32_16x16x32_bf16 v[92:95], v[128:131], v[198:201], v[92:95]
	v_mfma_f32_16x16x32_bf16 v[92:95], v[132:135], v[202:205], v[92:95]
	v_mfma_f32_16x16x32_bf16 v[84:87], v[152:155], v[198:201], v[84:87]
	v_mfma_f32_16x16x32_bf16 v[84:87], v[156:159], v[202:205], v[84:87]
	v_mfma_f32_16x16x32_bf16 v[76:79], v[128:131], v[206:209], v[76:79]
	v_mfma_f32_16x16x32_bf16 v[76:79], v[132:135], v[210:213], v[76:79]
	v_mfma_f32_16x16x32_bf16 v[68:71], v[152:155], v[206:209], v[68:71]
	v_mfma_f32_16x16x32_bf16 v[68:71], v[156:159], v[210:213], v[68:71]
	s_setprio 0
	s_setprio 1
	v_mfma_f32_16x16x32_bf16 v[120:123], v[160:163], v[182:185], v[120:123]
	v_mfma_f32_16x16x32_bf16 v[120:123], v[170:173], v[186:189], v[120:123]
	v_mfma_f32_16x16x32_bf16 v[112:115], v[174:177], v[182:185], v[112:115]
	v_mfma_f32_16x16x32_bf16 v[112:115], v[178:181], v[186:189], v[112:115]
	v_mfma_f32_16x16x32_bf16 v[104:107], v[160:163], v[190:193], v[104:107]
	v_mfma_f32_16x16x32_bf16 v[104:107], v[170:173], v[194:197], v[104:107]
	v_mfma_f32_16x16x32_bf16 v[96:99], v[174:177], v[190:193], v[96:99]
	v_mfma_f32_16x16x32_bf16 v[96:99], v[178:181], v[194:197], v[96:99]
	v_mfma_f32_16x16x32_bf16 v[88:91], v[160:163], v[198:201], v[88:91]
	v_mfma_f32_16x16x32_bf16 v[88:91], v[170:173], v[202:205], v[88:91]
	v_mfma_f32_16x16x32_bf16 v[80:83], v[174:177], v[198:201], v[80:83]
	v_mfma_f32_16x16x32_bf16 v[80:83], v[178:181], v[202:205], v[80:83]
	v_mfma_f32_16x16x32_bf16 v[72:75], v[160:163], v[206:209], v[72:75]
	v_mfma_f32_16x16x32_bf16 v[72:75], v[170:173], v[210:213], v[72:75]
	v_mfma_f32_16x16x32_bf16 v[64:67], v[174:177], v[206:209], v[64:67]
	v_mfma_f32_16x16x32_bf16 v[64:67], v[178:181], v[210:213], v[64:67]
	s_barrier
	s_setprio 0
	s_add_i32 s63, s63, s16
	v_lshl_add_u64 v[214:215], s[40:41], 0, v[140:141]
	s_mov_b32 m0, s63
	ds_read_b128 v[182:185], v168 offset:16384
	ds_read_b128 v[186:189], v168 offset:17408
	ds_read_b128 v[190:193], v168 offset:18432
	ds_read_b128 v[194:197], v168 offset:19456
	ds_read_b128 v[198:201], v168 offset:20480
	ds_read_b128 v[202:205], v168 offset:21504
	ds_read_b128 v[206:209], v168 offset:22528
	ds_read_b128 v[210:213], v168 offset:23552
	global_load_lds_dwordx4 v[214:215], off
	s_add_i32 m0, s63, 0x2000
	s_add_u32 s66, s40, 0x4000
	v_lshl_add_u64 v[214:215], s[40:41], 0, v[136:137]
	s_addc_u32 s67, s41, 0
	s_add_i32 s63, s75, s16
	global_load_lds_dwordx4 v[214:215], off
	v_lshl_add_u64 v[214:215], s[66:67], 0, v[140:141]
	s_mov_b32 m0, s63
	s_nop 0
	global_load_lds_dwordx4 v[214:215], off
	v_lshl_add_u64 v[214:215], s[66:67], 0, v[136:137]
	s_add_i32 m0, s63, 0x2000
	s_nop 0
	global_load_lds_dwordx4 v[214:215], off
	v_lshl_add_u64 v[214:215], s[42:43], 0, v[142:143]
	s_mov_b32 m0, s19
	s_nop 0
	global_load_lds_dwordx4 v[214:215], off
	v_lshl_add_u64 v[214:215], s[42:43], 0, v[138:139]
	s_mov_b32 m0, s20
	s_nop 0
	global_load_lds_dwordx4 v[214:215], off
	s_setprio 1
	s_waitcnt vmcnt(8)
	s_waitcnt lgkmcnt(0)
	s_barrier
; #define PG8_STAGE(bufoff, gbase, voff) do { _Pragma("unroll") for (int _i = 0; _i < 2; ++_i) \
;         __builtin_amdgcn_global_load_lds((const unsigned*)((const char*)(gbase) + (voff)[_i]), (PG8_LAS unsigned*)(lds + (bufoff) + ldsw + _i * 8192), 16, 0, 0); } while (0)
; #define PG8_LDA(dst, b, h) do { _Pragma("unroll") for (int m = 0; m < 4; ++m) _Pragma("unroll") for (int k = 0; k < 2; ++k) dst[m][k] = *(const PG8_LAS bf16x8*)(lds + PG8_SA(b, h) + aoff + m * 2048 + k * 1024); } while (0)
; #define PG8_LDB(dst, b, h) do { _Pragma("unroll") for (int n = 0; n < 2; ++n) _Pragma("unroll") for (int k = 0; k < 2; ++k) dst[n][k] = *(const PG8_LAS bf16x8*)(lds + PG8_SB(b, h) + boff + n * 2048 + k * 1024); } while (0)
; #define PG8_MMA(ai, bj, At, Bt) do { __builtin_amdgcn_s_setprio(1); _Pragma("unroll") for (int m = 0; m < 4; ++m) _Pragma("unroll") for (int n = 0; n < 2; ++n) _Pragma("unroll") for (int k = 0; k < 2; ++k) \
;         acc[ai][bj][m][n] = __builtin_amdgcn_mfma_f32_16x16x32_bf16(Bt[n][k], At[m][k], acc[ai][bj][m][n], 0, 0, 0); __builtin_amdgcn_s_setprio(0); } while (0)
; #define PG8_WAIT_V(n) asm volatile("s_waitcnt vmcnt(" #n ")" ::: "memory")
; #define PG8_WAIT_L(n) asm volatile("s_waitcnt lgkmcnt(" #n ")" ::: "memory")
; #define PG8_BAR __builtin_amdgcn_s_barrier()
; #define PG8_SCHED __builtin_amdgcn_sched_barrier(0)
; template <class Epi, class Sched, bool ALIGN_EPI = false, bool SP2 = false>
; __device__ __forceinline__ void gemm_phase(PG8_LAS unsigned char* lds, const Gemm g, const Sched& S, const Epi& E) {
;     ...
;             PG8_WAIT_V(8); PG8_WAIT_L(0); PG8_BAR; PG8_MMA(1, 0, At, B0); PG8_MMA(1, 1, At, B1); PG8_BAR; PG8_SCHED;
;             PG8_LDB(B0, 1, 0); PG8_LDB(B1, 1, 1); PG8_SCHED; PG8_LDA(At, 1, 0); PG8_STAGE(PG8_SA(0, 1), a2 + hstepB, voffA);
;             PG8_WAIT_V(8); PG8_WAIT_L(0); PG8_BAR; PG8_MMA(0, 0, At, B0); PG8_MMA(0, 1, At, B1); PG8_BAR; PG8_SCHED;
	v_mfma_f32_16x16x32_bf16 v[60:63], v[128:131], v[182:185], v[60:63]
	v_mfma_f32_16x16x32_bf16 v[60:63], v[132:135], v[186:189], v[60:63]
	v_mfma_f32_16x16x32_bf16 v[52:55], v[152:155], v[182:185], v[52:55]
	v_mfma_f32_16x16x32_bf16 v[52:55], v[156:159], v[186:189], v[52:55]
	v_mfma_f32_16x16x32_bf16 v[44:47], v[128:131], v[190:193], v[44:47]
	v_mfma_f32_16x16x32_bf16 v[44:47], v[132:135], v[194:197], v[44:47]
	v_mfma_f32_16x16x32_bf16 v[36:39], v[152:155], v[190:193], v[36:39]
	v_mfma_f32_16x16x32_bf16 v[36:39], v[156:159], v[194:197], v[36:39]
	v_mfma_f32_16x16x32_bf16 v[28:31], v[128:131], v[198:201], v[28:31]
	v_mfma_f32_16x16x32_bf16 v[28:31], v[132:135], v[202:205], v[28:31]
	v_mfma_f32_16x16x32_bf16 v[20:23], v[152:155], v[198:201], v[20:23]
	v_mfma_f32_16x16x32_bf16 v[20:23], v[156:159], v[202:205], v[20:23]
	v_mfma_f32_16x16x32_bf16 v[12:15], v[128:131], v[206:209], v[12:15]
	v_mfma_f32_16x16x32_bf16 v[12:15], v[132:135], v[210:213], v[12:15]
	v_mfma_f32_16x16x32_bf16 v[4:7], v[152:155], v[206:209], v[4:7]
	v_mfma_f32_16x16x32_bf16 v[4:7], v[156:159], v[210:213], v[4:7]
	s_setprio 0
	s_setprio 1
	v_mfma_f32_16x16x32_bf16 v[56:59], v[160:163], v[182:185], v[56:59]
	v_mfma_f32_16x16x32_bf16 v[56:59], v[170:173], v[186:189], v[56:59]
	v_mfma_f32_16x16x32_bf16 v[48:51], v[174:177], v[182:185], v[48:51]
	v_mfma_f32_16x16x32_bf16 v[48:51], v[178:181], v[186:189], v[48:51]
	v_mfma_f32_16x16x32_bf16 v[40:43], v[160:163], v[190:193], v[40:43]
	v_mfma_f32_16x16x32_bf16 v[40:43], v[170:173], v[194:197], v[40:43]
	v_mfma_f32_16x16x32_bf16 v[32:35], v[174:177], v[190:193], v[32:35]
	v_mfma_f32_16x16x32_bf16 v[32:35], v[178:181], v[194:197], v[32:35]
	v_mfma_f32_16x16x32_bf16 v[24:27], v[160:163], v[198:201], v[24:27]
	v_mfma_f32_16x16x32_bf16 v[24:27], v[170:173], v[202:205], v[24:27]
	v_mfma_f32_16x16x32_bf16 v[16:19], v[174:177], v[198:201], v[16:19]
	v_mfma_f32_16x16x32_bf16 v[16:19], v[178:181], v[202:205], v[16:19]
	v_mfma_f32_16x16x32_bf16 v[8:11], v[160:163], v[206:209], v[8:11]
	v_mfma_f32_16x16x32_bf16 v[8:11], v[170:173], v[210:213], v[8:11]
	v_mfma_f32_16x16x32_bf16 v[0:3], v[174:177], v[206:209], v[0:3]
	v_mfma_f32_16x16x32_bf16 v[0:3], v[178:181], v[210:213], v[0:3]
	s_barrier
	s_setprio 0
	s_add_i32 s63, 0, 0x18000
	v_add_u32_e32 v151, s63, v165
	s_add_i32 s66, 0, 0x1c000
	ds_read_b128 v[128:131], v151
	ds_read_b128 v[132:135], v151 offset:1024
	ds_read_b128 v[152:155], v151 offset:2048
	ds_read_b128 v[156:159], v151 offset:3072
	v_add_u32_e32 v151, s66, v165
	ds_read_b128 v[160:163], v151
	ds_read_b128 v[170:173], v151 offset:1024
	ds_read_b128 v[174:177], v151 offset:2048
	ds_read_b128 v[178:181], v151 offset:3072
	s_add_u32 s42, s42, 0x4000
	s_addc_u32 s43, s43, 0
	s_mov_b32 m0, s21
	v_lshl_add_u64 v[214:215], s[42:43], 0, v[142:143]
	ds_read_b128 v[182:185], v168 offset:32768
	ds_read_b128 v[186:189], v168 offset:33792
	ds_read_b128 v[190:193], v168 offset:34816
	ds_read_b128 v[194:197], v168 offset:35840
	ds_read_b128 v[198:201], v168 offset:36864
	ds_read_b128 v[202:205], v168 offset:37888
	ds_read_b128 v[206:209], v168 offset:38912
	ds_read_b128 v[210:213], v168 offset:39936
	global_load_lds_dwordx4 v[214:215], off
	v_lshl_add_u64 v[214:215], s[42:43], 0, v[138:139]
	s_mov_b32 m0, s22
	s_nop 0
	global_load_lds_dwordx4 v[214:215], off
	s_setprio 1
	s_waitcnt vmcnt(8)
	s_waitcnt lgkmcnt(0)
	s_barrier
	v_mfma_f32_16x16x32_bf16 v[124:127], v[128:131], v[182:185], v[124:127]
	v_mfma_f32_16x16x32_bf16 v[124:127], v[132:135], v[186:189], v[124:127]
	v_mfma_f32_16x16x32_bf16 v[116:119], v[152:155], v[182:185], v[116:119]
	v_mfma_f32_16x16x32_bf16 v[116:119], v[156:159], v[186:189], v[116:119]
	v_mfma_f32_16x16x32_bf16 v[108:111], v[128:131], v[190:193], v[108:111]
	v_mfma_f32_16x16x32_bf16 v[108:111], v[132:135], v[194:197], v[108:111]
	v_mfma_f32_16x16x32_bf16 v[100:103], v[152:155], v[190:193], v[100:103]
	v_mfma_f32_16x16x32_bf16 v[100:103], v[156:159], v[194:197], v[100:103]
	v_mfma_f32_16x16x32_bf16 v[92:95], v[128:131], v[198:201], v[92:95]
	v_mfma_f32_16x16x32_bf16 v[92:95], v[132:135], v[202:205], v[92:95]
	v_mfma_f32_16x16x32_bf16 v[84:87], v[152:155], v[198:201], v[84:87]
	v_mfma_f32_16x16x32_bf16 v[84:87], v[156:159], v[202:205], v[84:87]
	v_mfma_f32_16x16x32_bf16 v[76:79], v[128:131], v[206:209], v[76:79]
	v_mfma_f32_16x16x32_bf16 v[76:79], v[132:135], v[210:213], v[76:79]
	v_mfma_f32_16x16x32_bf16 v[68:71], v[152:155], v[206:209], v[68:71]
	v_mfma_f32_16x16x32_bf16 v[68:71], v[156:159], v[210:213], v[68:71]
	s_setprio 0
	s_setprio 1
	v_mfma_f32_16x16x32_bf16 v[120:123], v[160:163], v[182:185], v[120:123]
	v_mfma_f32_16x16x32_bf16 v[120:123], v[170:173], v[186:189], v[120:123]
	v_mfma_f32_16x16x32_bf16 v[112:115], v[174:177], v[182:185], v[112:115]
	v_mfma_f32_16x16x32_bf16 v[112:115], v[178:181], v[186:189], v[112:115]
	v_mfma_f32_16x16x32_bf16 v[104:107], v[160:163], v[190:193], v[104:107]
	v_mfma_f32_16x16x32_bf16 v[104:107], v[170:173], v[194:197], v[104:107]
	v_mfma_f32_16x16x32_bf16 v[96:99], v[174:177], v[190:193], v[96:99]
	v_mfma_f32_16x16x32_bf16 v[96:99], v[178:181], v[194:197], v[96:99]
	v_mfma_f32_16x16x32_bf16 v[88:91], v[160:163], v[198:201], v[88:91]
	v_mfma_f32_16x16x32_bf16 v[88:91], v[170:173], v[202:205], v[88:91]
	v_mfma_f32_16x16x32_bf16 v[80:83], v[174:177], v[198:201], v[80:83]
	v_mfma_f32_16x16x32_bf16 v[80:83], v[178:181], v[202:205], v[80:83]
	v_mfma_f32_16x16x32_bf16 v[72:75], v[160:163], v[206:209], v[72:75]
	v_mfma_f32_16x16x32_bf16 v[72:75], v[170:173], v[210:213], v[72:75]
	v_mfma_f32_16x16x32_bf16 v[64:67], v[174:177], v[206:209], v[64:67]
	v_mfma_f32_16x16x32_bf16 v[64:67], v[178:181], v[210:213], v[64:67]
	s_barrier
; #define PG8_STAGE(bufoff, gbase, voff) do { _Pragma("unroll") for (int _i = 0; _i < 2; ++_i) \
;         __builtin_amdgcn_global_load_lds((const unsigned*)((const char*)(gbase) + (voff)[_i]), (PG8_LAS unsigned*)(lds + (bufoff) + ldsw + _i * 8192), 16, 0, 0); } while (0)
; #define PG8_LDA(dst, b, h) do { _Pragma("unroll") for (int m = 0; m < 4; ++m) _Pragma("unroll") for (int k = 0; k < 2; ++k) dst[m][k] = *(const PG8_LAS bf16x8*)(lds + PG8_SA(b, h) + aoff + m * 2048 + k * 1024); } while (0)
; #define PG8_MMA(ai, bj, At, Bt) do { __builtin_amdgcn_s_setprio(1); _Pragma("unroll") for (int m = 0; m < 4; ++m) _Pragma("unroll") for (int n = 0; n < 2; ++n) _Pragma("unroll") for (int k = 0; k < 2; ++k) \
;         acc[ai][bj][m][n] = __builtin_amdgcn_mfma_f32_16x16x32_bf16(Bt[n][k], At[m][k], acc[ai][bj][m][n], 0, 0, 0); __builtin_amdgcn_s_setprio(0); } while (0)
; #define PG8_WAIT_V(n) asm volatile("s_waitcnt vmcnt(" #n ")" ::: "memory")
; #define PG8_WAIT_L(n) asm volatile("s_waitcnt lgkmcnt(" #n ")" ::: "memory")
; #define PG8_BAR __builtin_amdgcn_s_barrier()
; #define PG8_SCHED __builtin_amdgcn_sched_barrier(0)
; template <class Epi, class Sched, bool ALIGN_EPI = false, bool SP2 = false>
; __device__ __forceinline__ void gemm_phase(PG8_LAS unsigned char* lds, const Gemm g, const Sched& S, const Epi& E) {
;     ...
;             PG8_LDA(At, 1, 1); PG8_STAGE(PG8_SB(1, 0), b3, voffB); PG8_STAGE(PG8_SB(1, 1), b3 + hstepB, voffB); PG8_STAGE(PG8_SA(1, 0), a3, voffA);
;             PG8_WAIT_V(8); PG8_WAIT_L(0); PG8_BAR; PG8_MMA(1, 0, At, B0); PG8_MMA(1, 1, At, B1); PG8_BAR; PG8_SCHED;
;     ...
;         if constexpr (ALIGN_EPI) { if (wr == 0) PG8_BAR; }
	s_setprio 0
	s_add_u32 s42, s40, 0x8000
	s_addc_u32 s43, s41, 0
	s_add_i32 s63, s63, s16
	v_lshl_add_u64 v[214:215], s[42:43], 0, v[140:141]
	s_mov_b32 m0, s63
	ds_read_b128 v[182:185], v168 offset:49152
	ds_read_b128 v[186:189], v168 offset:50176
	ds_read_b128 v[190:193], v168 offset:51200
	ds_read_b128 v[194:197], v168 offset:52224
	ds_read_b128 v[198:201], v168 offset:53248
	ds_read_b128 v[202:205], v168 offset:54272
	ds_read_b128 v[206:209], v168 offset:55296
	ds_read_b128 v[210:213], v168 offset:56320
	global_load_lds_dwordx4 v[214:215], off
	s_add_i32 m0, s63, 0x2000
	s_add_u32 s40, s40, 0xc000
	v_lshl_add_u64 v[214:215], s[42:43], 0, v[136:137]
	s_addc_u32 s41, s41, 0
	s_add_i32 s42, s66, s16
	global_load_lds_dwordx4 v[214:215], off
	v_lshl_add_u64 v[214:215], s[40:41], 0, v[140:141]
	s_mov_b32 m0, s42
	s_nop 0
	global_load_lds_dwordx4 v[214:215], off
	v_lshl_add_u64 v[214:215], s[40:41], 0, v[136:137]
	s_add_i32 m0, s42, 0x2000
	s_nop 0
	global_load_lds_dwordx4 v[214:215], off
	v_lshl_add_u64 v[214:215], s[38:39], 0, v[142:143]
	s_mov_b32 m0, s25
	s_nop 0
	global_load_lds_dwordx4 v[214:215], off
	v_lshl_add_u64 v[214:215], s[38:39], 0, v[138:139]
	s_mov_b32 m0, s26
	s_nop 0
	global_load_lds_dwordx4 v[214:215], off
	s_setprio 1
	s_waitcnt vmcnt(8)
	s_waitcnt lgkmcnt(0)
	s_barrier
	v_mfma_f32_16x16x32_bf16 v[60:63], v[128:131], v[182:185], v[60:63]
	v_mfma_f32_16x16x32_bf16 v[60:63], v[132:135], v[186:189], v[60:63]
	v_mfma_f32_16x16x32_bf16 v[52:55], v[152:155], v[182:185], v[52:55]
	v_mfma_f32_16x16x32_bf16 v[52:55], v[156:159], v[186:189], v[52:55]
	v_mfma_f32_16x16x32_bf16 v[44:47], v[128:131], v[190:193], v[44:47]
	v_mfma_f32_16x16x32_bf16 v[44:47], v[132:135], v[194:197], v[44:47]
	v_mfma_f32_16x16x32_bf16 v[36:39], v[152:155], v[190:193], v[36:39]
	v_mfma_f32_16x16x32_bf16 v[36:39], v[156:159], v[194:197], v[36:39]
	v_mfma_f32_16x16x32_bf16 v[28:31], v[128:131], v[198:201], v[28:31]
	v_mfma_f32_16x16x32_bf16 v[28:31], v[132:135], v[202:205], v[28:31]
	v_mfma_f32_16x16x32_bf16 v[20:23], v[152:155], v[198:201], v[20:23]
	v_mfma_f32_16x16x32_bf16 v[20:23], v[156:159], v[202:205], v[20:23]
	v_mfma_f32_16x16x32_bf16 v[12:15], v[128:131], v[206:209], v[12:15]
	v_mfma_f32_16x16x32_bf16 v[12:15], v[132:135], v[210:213], v[12:15]
	v_mfma_f32_16x16x32_bf16 v[4:7], v[152:155], v[206:209], v[4:7]
	v_mfma_f32_16x16x32_bf16 v[4:7], v[156:159], v[210:213], v[4:7]
	s_setprio 0
	s_setprio 1
	v_mfma_f32_16x16x32_bf16 v[56:59], v[160:163], v[182:185], v[56:59]
	v_mfma_f32_16x16x32_bf16 v[56:59], v[170:173], v[186:189], v[56:59]
	v_mfma_f32_16x16x32_bf16 v[48:51], v[174:177], v[182:185], v[48:51]
	v_mfma_f32_16x16x32_bf16 v[48:51], v[178:181], v[186:189], v[48:51]
	v_mfma_f32_16x16x32_bf16 v[40:43], v[160:163], v[190:193], v[40:43]
	v_mfma_f32_16x16x32_bf16 v[40:43], v[170:173], v[194:197], v[40:43]
	v_mfma_f32_16x16x32_bf16 v[32:35], v[174:177], v[190:193], v[32:35]
	v_mfma_f32_16x16x32_bf16 v[32:35], v[178:181], v[194:197], v[32:35]
	v_mfma_f32_16x16x32_bf16 v[24:27], v[160:163], v[198:201], v[24:27]
	v_mfma_f32_16x16x32_bf16 v[24:27], v[170:173], v[202:205], v[24:27]
	v_mfma_f32_16x16x32_bf16 v[16:19], v[174:177], v[198:201], v[16:19]
	v_mfma_f32_16x16x32_bf16 v[16:19], v[178:181], v[202:205], v[16:19]
	v_mfma_f32_16x16x32_bf16 v[8:11], v[160:163], v[206:209], v[8:11]
	v_mfma_f32_16x16x32_bf16 v[8:11], v[170:173], v[210:213], v[8:11]
	v_mfma_f32_16x16x32_bf16 v[0:3], v[174:177], v[206:209], v[0:3]
	v_mfma_f32_16x16x32_bf16 v[0:3], v[178:181], v[210:213], v[0:3]
	s_barrier
	s_setprio 0
	s_add_i32 s62, s62, 2
	s_add_u32 s36, s36, 0x10000
	s_addc_u32 s37, s37, 0
	s_add_u32 s44, s44, 0x10000
	s_addc_u32 s45, s45, 0
	s_cmp_gt_u32 s62, 29
	s_cbranch_scc0 .LBB0_263
	s_and_b64 vcc, exec, s[8:9]
	s_cbranch_vccz .LBB0_266
	s_barrier
